# GLA prep token loop: low-rank LDS reads issued one token ahead, the two log-sigmoid chains interleaved (no s_nop pads)
# speedup vs baseline: 1.0074x; 1.0047x over previous
.LBB0_225:
	s_ashr_i32 s0, s58, 3
	s_mul_hi_i32 s1, s0, 0x38e38e39
	s_lshr_b32 s4, s1, 31
	s_ashr_i32 s1, s1, 3
	s_add_i32 s1, s1, s4
	s_mul_i32 s4, s1, 36
	s_sub_i32 s21, s0, s4
	s_lshl_b32 s0, s21, 6
	s_mul_hi_i32 s4, s1, 0x900
	s_mulk_i32 s1, 0x900
	s_ashr_i32 s5, s0, 31
	s_add_u32 s0, s1, s0
	s_addc_u32 s1, s4, s5
	v_lshl_add_u64 v[10:11], s[0:1], 0, v[28:29]
	s_and_b32 s4, s44, 0x180
	v_lshlrev_b64 v[2:3], 11, v[10:11]
	v_lshl_add_u64 v[2:3], s[46:47], 0, v[2:3]
	s_lshl_b32 s92, s4, 1
	v_lshl_add_u64 v[2:3], v[2:3], 0, s[92:93]
	v_lshl_add_u64 v[6:7], v[2:3], 0, v[0:1]
	s_waitcnt lgkmcnt(0)
	s_barrier
	global_load_dwordx4 v[200:203], v[6:7], off
	s_nop 0
	global_load_dwordx4 v[204:207], v[6:7], off offset:1024
	v_lshl_add_u64 v[12:13], s[0:1], 0, v[30:31]
	v_lshl_add_u64 v[14:15], s[0:1], 0, v[32:33]
	v_lshl_add_u64 v[16:17], s[0:1], 0, v[34:35]
	v_lshlrev_b64 v[2:3], 11, v[12:13]
	v_lshl_add_u64 v[2:3], s[46:47], 0, v[2:3]
	v_lshl_add_u64 v[2:3], v[2:3], 0, s[92:93]
	v_lshl_add_u64 v[2:3], v[2:3], 0, v[0:1]
	global_load_dwordx4 v[208:211], v[2:3], off
	global_load_dwordx4 v[212:215], v[2:3], off offset:1024
	v_lshlrev_b64 v[2:3], 11, v[14:15]
	v_lshl_add_u64 v[2:3], s[46:47], 0, v[2:3]
	v_lshl_add_u64 v[2:3], v[2:3], 0, s[92:93]
	v_lshl_add_u64 v[2:3], v[2:3], 0, v[0:1]
	global_load_dwordx4 v[216:219], v[2:3], off
	global_load_dwordx4 v[220:223], v[2:3], off offset:1024
	v_lshlrev_b64 v[2:3], 11, v[16:17]
	v_lshl_add_u64 v[2:3], s[46:47], 0, v[2:3]
	v_lshl_add_u64 v[2:3], v[2:3], 0, s[92:93]
	v_lshl_add_u64 v[2:3], v[2:3], 0, v[0:1]
	global_load_dwordx4 v[224:227], v[2:3], off
	global_load_dwordx4 v[228:231], v[2:3], off offset:1024
	s_and_b32 s90, s58, 1
	s_or_b32 s88, s90, s2
	s_ashr_i32 s89, s88, 31
	v_readlane_b32 s60, v253, 20
	s_lshl_b64 s[0:1], s[88:89], 15
	v_readlane_b32 s66, v253, 26
	v_readlane_b32 s67, v253, 27
	v_readlane_b32 s68, v253, 28
	v_readlane_b32 s69, v253, 29
	v_readlane_b32 s61, v253, 21
	v_readlane_b32 s62, v253, 22
	v_readlane_b32 s63, v253, 23
	v_readlane_b32 s64, v253, 24
	v_readlane_b32 s65, v253, 25
	v_readlane_b32 s70, v253, 30
	v_readlane_b32 s71, v253, 31
	v_readlane_b32 s72, v253, 32
	v_readlane_b32 s73, v253, 33
	v_readlane_b32 s74, v253, 34
	v_readlane_b32 s75, v253, 35
	s_lshl_b32 s92, s90, 5
	s_add_u32 s0, s66, s0
	s_addc_u32 s1, s67, s1
	s_lshl_b32 s5, s4, 2
	s_add_u32 s0, s0, s5
	s_addc_u32 s1, s1, 0
	v_lshl_add_u64 v[2:3], v[24:25], 0, s[92:93]
	v_lshlrev_b64 v[4:5], 6, v[10:11]
	v_lshl_add_u64 v[4:5], v[2:3], 0, v[4:5]
	global_load_ushort v232, v[4:5], off
	v_lshlrev_b64 v[4:5], 6, v[12:13]
	v_lshl_add_u64 v[4:5], v[2:3], 0, v[4:5]
	global_load_ushort v233, v[4:5], off
	v_lshlrev_b64 v[4:5], 6, v[14:15]
	v_lshl_add_u64 v[4:5], v[2:3], 0, v[4:5]
	global_load_ushort v234, v[4:5], off
	v_lshlrev_b64 v[4:5], 6, v[16:17]
	v_lshl_add_u64 v[2:3], v[2:3], 0, v[4:5]
	global_load_ushort v235, v[2:3], off
	v_mov_b32_e32 v3, v1
	v_lshlrev_b32_e32 v2, 2, v20
	v_lshl_add_u64 v[4:5], s[0:1], 0, v[2:3]
	global_load_dword v60, v2, s[0:1]
	global_load_dword v61, v2, s[0:1] offset:256
	global_load_dword v62, v2, s[0:1] offset:2048
	global_load_dword v63, v2, s[0:1] offset:2304
	v_add_co_u32_e64 v2, s[0:1], s85, v4
	s_nop 1
	v_addc_co_u32_e64 v3, s[0:1], 0, v5, s[0:1]
	v_add_co_u32_e64 v6, s[0:1], s37, v4
	s_nop 1
	v_addc_co_u32_e64 v7, s[0:1], 0, v5, s[0:1]
	global_load_dword v64, v[6:7], off offset:-4096
	global_load_dword v65, v[2:3], off offset:256
	global_load_dword v66, v[2:3], off offset:2048
	global_load_dword v67, v[2:3], off offset:2304
	global_load_dword v47, v[6:7], off
	global_load_dword v46, v[6:7], off offset:256
	global_load_dword v17, v[6:7], off offset:2048
	global_load_dword v16, v[6:7], off offset:2304
	v_add_co_u32_e64 v2, s[0:1], s33, v4
	s_nop 1
	v_addc_co_u32_e64 v3, s[0:1], 0, v5, s[0:1]
	s_movk_i32 s0, 0x4000
	s_nop 0
	v_add_co_u32_e64 v6, s[0:1], s0, v4
	s_nop 1
	v_addc_co_u32_e64 v7, s[0:1], 0, v5, s[0:1]
	s_movk_i32 s0, 0x5000
	global_load_dword v52, v[6:7], off offset:-4096
	global_load_dword v53, v[2:3], off offset:256
	global_load_dword v54, v[2:3], off offset:2048
	global_load_dword v55, v[2:3], off offset:2304
	global_load_dword v48, v[6:7], off
	global_load_dword v49, v[6:7], off offset:256
	global_load_dword v50, v[6:7], off offset:2048
	global_load_dword v51, v[6:7], off offset:2304
	v_add_co_u32_e64 v2, s[0:1], s0, v4
	s_nop 1
	v_addc_co_u32_e64 v3, s[0:1], 0, v5, s[0:1]
	s_movk_i32 s0, 0x6000
	s_nop 0
	v_add_co_u32_e64 v8, s[0:1], s0, v4
	s_nop 1
	v_addc_co_u32_e64 v9, s[0:1], 0, v5, s[0:1]
	s_movk_i32 s0, 0x7000
	global_load_dword v56, v[8:9], off offset:-4096
	global_load_dword v57, v[2:3], off offset:256
	global_load_dword v58, v[2:3], off offset:2048
	global_load_dword v59, v[2:3], off offset:2304
	global_load_dword v12, v[8:9], off
	global_load_dword v13, v[8:9], off offset:256
	global_load_dword v6, v[8:9], off offset:2048
	global_load_dword v7, v[8:9], off offset:2304
	v_add_co_u32_e64 v2, s[0:1], s0, v4
	s_nop 1
	v_addc_co_u32_e64 v3, s[0:1], 0, v5, s[0:1]
	s_lshl_b32 s0, s88, 9
	s_or_b32 s0, s0, s4
	global_load_dword v14, v[2:3], off
	global_load_dword v15, v[2:3], off offset:256
	global_load_dword v9, v[2:3], off offset:2048
	global_load_dword v10, v[2:3], off offset:2304
	v_or_b32_e32 v2, s0, v20
	v_ashrrev_i32_e32 v3, 31, v2
	v_lshl_add_u64 v[2:3], v[2:3], 2, s[68:69]
	global_load_dword v69, v[2:3], off
	global_load_dword v68, v[2:3], off offset:256
	s_waitcnt vmcnt(34)
	ds_write_b128 v82, v[200:203]
	ds_write_b128 v82, v[204:207] offset:16384
	ds_write_b128 v85, v[208:211]
	ds_write_b128 v85, v[212:215] offset:16384
	ds_write_b128 v88, v[216:219]
	ds_write_b128 v88, v[220:223] offset:16384
	ds_write_b128 v91, v[224:227]
	ds_write_b128 v91, v[228:231] offset:16384
	v_lshlrev_b32_e32 v236, 16, v232
	v_lshlrev_b32_e32 v237, 16, v233
	ds_write2st64_b32 v18, v236, v237 offset0:128 offset1:132
	v_lshlrev_b32_e32 v238, 16, v234
	v_lshlrev_b32_e32 v239, 16, v235
	ds_write2st64_b32 v18, v238, v239 offset0:136 offset1:140
	s_waitcnt lgkmcnt(0)
	s_barrier
	ds_read_b128 v[2:5], v19 offset:32768
	ds_read_b128 v[156:159], v19 offset:32784
	ds_read_b128 v[160:163], v19 offset:32800
	ds_read_b128 v[164:167], v19 offset:32816
	s_waitcnt vmcnt(1) lgkmcnt(3)
	v_fma_f32 v8, v60, v2, v69
	v_fmac_f32_e32 v8, v62, v3
	v_fmac_f32_e32 v8, v64, v4
	v_fmac_f32_e32 v8, v66, v5
	s_waitcnt lgkmcnt(2)
	v_fmac_f32_e32 v8, v47, v156
	v_fmac_f32_e32 v8, v17, v157
	v_fmac_f32_e32 v8, v52, v158
	v_fmac_f32_e32 v8, v54, v159
	s_waitcnt lgkmcnt(1)
	v_fmac_f32_e32 v8, v48, v160
	v_fmac_f32_e32 v8, v50, v161
	v_fmac_f32_e32 v8, v56, v162
	v_fmac_f32_e32 v8, v58, v163
	s_waitcnt lgkmcnt(0)
	v_fmac_f32_e32 v8, v12, v164
	v_fmac_f32_e32 v8, v6, v165
	s_waitcnt vmcnt(0)
	v_fma_f32 v2, v61, v2, v68
	v_fmac_f32_e32 v8, v14, v166
	v_fmac_f32_e32 v2, v63, v3
	v_fmac_f32_e32 v8, v9, v167
	v_fmac_f32_e32 v2, v65, v4
	v_mul_f32_e64 v4, |v8|, s84
	v_exp_f32_e32 v4, v4
	v_fmac_f32_e32 v2, v67, v5
	v_fmac_f32_e32 v2, v46, v156
	v_fmac_f32_e32 v2, v16, v157
	v_add_f32_e32 v4, 1.0, v4
	v_cmp_gt_f32_e64 s[0:1], s31, v4
	v_fmac_f32_e32 v2, v53, v158
	v_fmac_f32_e32 v2, v55, v159
	v_cndmask_b32_e64 v5, 0, 32, s[0:1]
	v_ldexp_f32 v4, v4, v5
	v_log_f32_e32 v4, v4
	v_fmac_f32_e32 v2, v49, v160
	v_fmac_f32_e32 v2, v51, v161
	v_fmac_f32_e32 v2, v57, v162
	v_mul_f32_e32 v5, 0x3f317217, v4
	v_fmac_f32_e32 v2, v59, v163
	v_fma_f32 v5, v4, s78, -v5
	v_fmac_f32_e32 v2, v13, v164
	v_fmac_f32_e32 v5, 0x3377d1cf, v4
	v_fmac_f32_e32 v2, v7, v165
	v_fmac_f32_e32 v5, 0x3f317217, v4
	v_cmp_lt_f32_e64 s[88:89], |v4|, s79
	v_fmac_f32_e32 v2, v15, v166
	v_fmac_f32_e32 v2, v10, v167
	v_cndmask_b32_e64 v4, v4, v5, s[88:89]
	v_cndmask_b32_e64 v5, 0, v198, s[0:1]
	v_min_f32_e32 v3, 0, v8
	v_sub_f32_e32 v4, v4, v5
	v_sub_f32_e32 v70, v3, v4
	v_min_f32_e32 v3, 0, v2
	v_mul_f32_e64 v2, |v2|, s84
	v_exp_f32_e32 v2, v2
	v_fma_f32 v11, v70, s10, 0
	v_add_f32_e32 v2, 1.0, v2
	v_cmp_gt_f32_e64 s[0:1], s31, v2
	s_nop 1
	v_cndmask_b32_e64 v4, 0, 32, s[0:1]
	v_ldexp_f32 v2, v2, v4
	v_log_f32_e32 v2, v2
	s_nop 0
	v_mul_f32_e32 v4, 0x3f317217, v2
	v_fma_f32 v4, v2, s78, -v4
	v_fmac_f32_e32 v4, 0x3377d1cf, v2
	v_fmac_f32_e32 v4, 0x3f317217, v2
	v_cmp_lt_f32_e64 s[88:89], |v2|, s79
	s_nop 1
	v_cndmask_b32_e64 v2, v2, v4, s[88:89]
	v_cndmask_b32_e64 v4, 0, v198, s[0:1]
	v_sub_f32_e32 v2, v2, v4
	v_sub_f32_e32 v71, v3, v2
	ds_read_b128 v[2:5], v19 offset:32832
	v_fma_f32 v8, v71, s10, 0
	s_waitcnt lgkmcnt(0)
	v_fma_f32 v155, v60, v2, v69
	v_fma_f32 v156, v61, v2, v68
	v_fmac_f32_e32 v155, v62, v3
	v_fmac_f32_e32 v156, v63, v3
	v_fmac_f32_e32 v155, v64, v4
	v_fmac_f32_e32 v156, v65, v4
	v_fmac_f32_e32 v155, v66, v5
	v_fmac_f32_e32 v156, v67, v5
	ds_read_b128 v[2:5], v19 offset:32848
	s_waitcnt lgkmcnt(0)
	v_fmac_f32_e32 v155, v47, v2
	v_fmac_f32_e32 v156, v46, v2
	v_fmac_f32_e32 v155, v17, v3
	v_fmac_f32_e32 v156, v16, v3
	v_fmac_f32_e32 v155, v52, v4
	v_fmac_f32_e32 v156, v53, v4
	v_fmac_f32_e32 v155, v54, v5
	v_fmac_f32_e32 v156, v55, v5
	ds_read_b128 v[2:5], v19 offset:32864
	s_waitcnt lgkmcnt(0)
	v_fmac_f32_e32 v155, v48, v2
	v_fmac_f32_e32 v156, v49, v2
	v_fmac_f32_e32 v155, v50, v3
	v_fmac_f32_e32 v156, v51, v3
	v_fmac_f32_e32 v155, v56, v4
	v_fmac_f32_e32 v156, v57, v4
	v_fmac_f32_e32 v155, v58, v5
	v_fmac_f32_e32 v156, v59, v5
	ds_read_b128 v[2:5], v19 offset:32880
	s_waitcnt lgkmcnt(0)
	v_fmac_f32_e32 v155, v12, v2
	v_fmac_f32_e32 v155, v6, v3
	v_fmac_f32_e32 v155, v14, v4
	v_fmac_f32_e32 v156, v13, v2
	v_fmac_f32_e32 v155, v9, v5
	v_fmac_f32_e32 v156, v7, v3
	v_mul_f32_e64 v3, |v155|, s84
	v_exp_f32_e32 v3, v3
	v_fmac_f32_e32 v156, v15, v4
	v_fmac_f32_e32 v156, v10, v5
	v_min_f32_e32 v2, 0, v155
	v_add_f32_e32 v3, 1.0, v3
	v_cmp_gt_f32_e64 s[0:1], s31, v3
	s_nop 1
	v_cndmask_b32_e64 v4, 0, 32, s[0:1]
	v_ldexp_f32 v3, v3, v4
	v_log_f32_e32 v3, v3
	s_nop 0
	v_mul_f32_e32 v4, 0x3f317217, v3
	v_fma_f32 v4, v3, s78, -v4
	v_fmac_f32_e32 v4, 0x3377d1cf, v3
	v_fmac_f32_e32 v4, 0x3f317217, v3
	v_cmp_lt_f32_e64 s[88:89], |v3|, s79
	s_nop 1
	v_cndmask_b32_e64 v3, v3, v4, s[88:89]
	v_cndmask_b32_e64 v4, 0, v198, s[0:1]
	v_sub_f32_e32 v3, v3, v4
	v_sub_f32_e32 v159, v2, v3
	v_mul_f32_e64 v3, |v156|, s84
	v_exp_f32_e32 v3, v3
	v_min_f32_e32 v2, 0, v156
	v_fmamk_f32 v156, v159, 0x3d800000, v11
	v_add_f32_e32 v3, 1.0, v3
	v_cmp_gt_f32_e64 s[0:1], s31, v3
	s_nop 1
	v_cndmask_b32_e64 v4, 0, 32, s[0:1]
	v_ldexp_f32 v3, v3, v4
	v_log_f32_e32 v3, v3
	s_nop 0
	v_mul_f32_e32 v4, 0x3f317217, v3
	v_fma_f32 v4, v3, s78, -v4
	v_fmac_f32_e32 v4, 0x3377d1cf, v3
	v_fmac_f32_e32 v4, 0x3f317217, v3
	v_cmp_lt_f32_e64 s[88:89], |v3|, s79
	s_nop 1
	v_cndmask_b32_e64 v3, v3, v4, s[88:89]
	v_cndmask_b32_e64 v4, 0, v198, s[0:1]
	v_sub_f32_e32 v3, v3, v4
	v_sub_f32_e32 v160, v2, v3
	ds_read_b128 v[2:5], v19 offset:32896
	ds_read_b128 v[234:237], v19 offset:32912
	ds_read_b128 v[238:241], v19 offset:32928
	ds_read_b128 v[244:247], v19 offset:32944
	v_fmamk_f32 v155, v160, 0x3d800000, v8
	s_waitcnt lgkmcnt(3)
	v_fma_f32 v157, v60, v2, v69
	v_fma_f32 v158, v61, v2, v68
	v_fmac_f32_e32 v157, v62, v3
	v_fmac_f32_e32 v158, v63, v3
	v_fmac_f32_e32 v157, v64, v4
	v_fmac_f32_e32 v158, v65, v4
	v_fmac_f32_e32 v157, v66, v5
	v_fmac_f32_e32 v158, v67, v5
	s_waitcnt lgkmcnt(2)
	v_fmac_f32_e32 v157, v47, v234
	v_fmac_f32_e32 v158, v46, v234
	v_fmac_f32_e32 v157, v17, v235
	v_fmac_f32_e32 v158, v16, v235
	v_fmac_f32_e32 v157, v52, v236
	v_fmac_f32_e32 v158, v53, v236
	v_fmac_f32_e32 v157, v54, v237
	v_fmac_f32_e32 v158, v55, v237
	s_waitcnt lgkmcnt(1)
	v_fmac_f32_e32 v157, v48, v238
	v_fmac_f32_e32 v158, v49, v238
	v_fmac_f32_e32 v157, v50, v239
	v_fmac_f32_e32 v158, v51, v239
	v_fmac_f32_e32 v157, v56, v240
	v_fmac_f32_e32 v158, v57, v240
	v_fmac_f32_e32 v157, v58, v241
	v_fmac_f32_e32 v158, v59, v241
	s_waitcnt lgkmcnt(0)
	v_fmac_f32_e32 v157, v12, v244
	v_fmac_f32_e32 v158, v13, v244
	v_fmac_f32_e32 v157, v6, v245
	v_fmac_f32_e32 v158, v7, v245
	v_fmac_f32_e32 v157, v14, v246
	v_fmac_f32_e32 v158, v15, v246
	v_fmac_f32_e32 v157, v9, v247
	v_fmac_f32_e32 v158, v10, v247
	ds_read_b128 v[2:5], v19 offset:32960
	ds_read_b128 v[234:237], v19 offset:32976
	ds_read_b128 v[238:241], v19 offset:32992
	ds_read_b128 v[244:247], v19 offset:33008
	v_mul_f32_e64 v249, |v157|, s84
	v_mul_f32_e64 v231, |v158|, s84
	v_exp_f32_e32 v249, v249
	v_exp_f32_e32 v231, v231
	v_min_f32_e32 v248, 0, v157
	v_min_f32_e32 v230, 0, v158
	v_add_f32_e32 v249, 1.0, v249
	v_add_f32_e32 v231, 1.0, v231
	v_cmp_gt_f32_e64 s[0:1], s31, v249
	v_cmp_gt_f32_e64 s[100:101], s31, v231
	s_nop 0
	v_cndmask_b32_e64 v250, 0, 32, s[0:1]
	v_cndmask_b32_e64 v232, 0, 32, s[100:101]
	v_ldexp_f32 v249, v249, v250
	v_ldexp_f32 v231, v231, v232
	v_log_f32_e32 v249, v249
	v_log_f32_e32 v231, v231
	v_mul_f32_e32 v250, 0x3f317217, v249
	v_mul_f32_e32 v232, 0x3f317217, v231
	v_fma_f32 v250, v249, s78, -v250
	v_fma_f32 v232, v231, s78, -v232
	v_fmac_f32_e32 v250, 0x3377d1cf, v249
	v_fmac_f32_e32 v232, 0x3377d1cf, v231
	v_fmac_f32_e32 v250, 0x3f317217, v249
	v_fmac_f32_e32 v232, 0x3f317217, v231
	v_cmp_lt_f32_e64 s[88:89], |v249|, s79
	v_cndmask_b32_e64 v251, 0, v198, s[0:1]
	v_cndmask_b32_e64 v233, 0, v198, s[100:101]
	v_cndmask_b32_e64 v249, v249, v250, s[88:89]
	v_cmp_lt_f32_e64 s[88:89], |v231|, s79
	v_sub_f32_e32 v249, v249, v251
	v_sub_f32_e32 v163, v248, v249
	v_cndmask_b32_e64 v231, v231, v232, s[88:89]
	v_sub_f32_e32 v231, v231, v233
	v_sub_f32_e32 v164, v230, v231
	v_fmamk_f32 v158, v163, 0x3d800000, v156
	v_fmamk_f32 v157, v164, 0x3d800000, v155
	s_waitcnt lgkmcnt(3)
	v_fma_f32 v161, v60, v2, v69
	v_fma_f32 v162, v61, v2, v68
	v_fmac_f32_e32 v161, v62, v3
	v_fmac_f32_e32 v162, v63, v3
	v_fmac_f32_e32 v161, v64, v4
	v_fmac_f32_e32 v162, v65, v4
	v_fmac_f32_e32 v161, v66, v5
	v_fmac_f32_e32 v162, v67, v5
	s_waitcnt lgkmcnt(2)
	v_fmac_f32_e32 v161, v47, v234
	v_fmac_f32_e32 v162, v46, v234
	v_fmac_f32_e32 v161, v17, v235
	v_fmac_f32_e32 v162, v16, v235
	v_fmac_f32_e32 v161, v52, v236
	v_fmac_f32_e32 v162, v53, v236
	v_fmac_f32_e32 v161, v54, v237
	v_fmac_f32_e32 v162, v55, v237
	s_waitcnt lgkmcnt(1)
	v_fmac_f32_e32 v161, v48, v238
	v_fmac_f32_e32 v162, v49, v238
	v_fmac_f32_e32 v161, v50, v239
	v_fmac_f32_e32 v162, v51, v239
	v_fmac_f32_e32 v161, v56, v240
	v_fmac_f32_e32 v162, v57, v240
	v_fmac_f32_e32 v161, v58, v241
	v_fmac_f32_e32 v162, v59, v241
	s_waitcnt lgkmcnt(0)
	v_fmac_f32_e32 v161, v12, v244
	v_fmac_f32_e32 v162, v13, v244
	v_fmac_f32_e32 v161, v6, v245
	v_fmac_f32_e32 v162, v7, v245
	v_fmac_f32_e32 v161, v14, v246
	v_fmac_f32_e32 v162, v15, v246
	v_fmac_f32_e32 v161, v9, v247
	v_fmac_f32_e32 v162, v10, v247
	ds_read_b128 v[2:5], v19 offset:33024
	ds_read_b128 v[234:237], v19 offset:33040
	ds_read_b128 v[238:241], v19 offset:33056
	ds_read_b128 v[244:247], v19 offset:33072
	v_mul_f32_e64 v249, |v161|, s84
	v_mul_f32_e64 v231, |v162|, s84
	v_exp_f32_e32 v249, v249
	v_exp_f32_e32 v231, v231
	v_min_f32_e32 v248, 0, v161
	v_min_f32_e32 v230, 0, v162
	v_add_f32_e32 v249, 1.0, v249
	v_add_f32_e32 v231, 1.0, v231
	v_cmp_gt_f32_e64 s[0:1], s31, v249
	v_cmp_gt_f32_e64 s[100:101], s31, v231
	s_nop 0
	v_cndmask_b32_e64 v250, 0, 32, s[0:1]
	v_cndmask_b32_e64 v232, 0, 32, s[100:101]
	v_ldexp_f32 v249, v249, v250
	v_ldexp_f32 v231, v231, v232
	v_log_f32_e32 v249, v249
	v_log_f32_e32 v231, v231
	v_mul_f32_e32 v250, 0x3f317217, v249
	v_mul_f32_e32 v232, 0x3f317217, v231
	v_fma_f32 v250, v249, s78, -v250
	v_fma_f32 v232, v231, s78, -v232
	v_fmac_f32_e32 v250, 0x3377d1cf, v249
	v_fmac_f32_e32 v232, 0x3377d1cf, v231
	v_fmac_f32_e32 v250, 0x3f317217, v249
	v_fmac_f32_e32 v232, 0x3f317217, v231
	v_cmp_lt_f32_e64 s[88:89], |v249|, s79
	v_cndmask_b32_e64 v251, 0, v198, s[0:1]
	v_cndmask_b32_e64 v233, 0, v198, s[100:101]
	v_cndmask_b32_e64 v249, v249, v250, s[88:89]
	v_cmp_lt_f32_e64 s[88:89], |v231|, s79
	v_sub_f32_e32 v249, v249, v251
	v_sub_f32_e32 v165, v248, v249
	v_cndmask_b32_e64 v231, v231, v232, s[88:89]
	v_sub_f32_e32 v231, v231, v233
	v_sub_f32_e32 v166, v230, v231
	v_fmamk_f32 v162, v165, 0x3d800000, v158
	v_fmamk_f32 v161, v166, 0x3d800000, v157
	s_waitcnt lgkmcnt(3)
	v_fma_f32 v168, v60, v2, v69
	v_fma_f32 v167, v61, v2, v68
	v_fmac_f32_e32 v168, v62, v3
	v_fmac_f32_e32 v167, v63, v3
	v_fmac_f32_e32 v168, v64, v4
	v_fmac_f32_e32 v167, v65, v4
	v_fmac_f32_e32 v168, v66, v5
	v_fmac_f32_e32 v167, v67, v5
	s_waitcnt lgkmcnt(2)
	v_fmac_f32_e32 v168, v47, v234
	v_fmac_f32_e32 v167, v46, v234
	v_fmac_f32_e32 v168, v17, v235
	v_fmac_f32_e32 v167, v16, v235
	v_fmac_f32_e32 v168, v52, v236
	v_fmac_f32_e32 v167, v53, v236
	v_fmac_f32_e32 v168, v54, v237
	v_fmac_f32_e32 v167, v55, v237
	s_waitcnt lgkmcnt(1)
	v_fmac_f32_e32 v168, v48, v238
	v_fmac_f32_e32 v167, v49, v238
	v_fmac_f32_e32 v168, v50, v239
	v_fmac_f32_e32 v167, v51, v239
	v_fmac_f32_e32 v168, v56, v240
	v_fmac_f32_e32 v167, v57, v240
	v_fmac_f32_e32 v168, v58, v241
	v_fmac_f32_e32 v167, v59, v241
	s_waitcnt lgkmcnt(0)
	v_fmac_f32_e32 v168, v12, v244
	v_fmac_f32_e32 v167, v13, v244
	v_fmac_f32_e32 v168, v6, v245
	v_fmac_f32_e32 v167, v7, v245
	v_fmac_f32_e32 v168, v14, v246
	v_fmac_f32_e32 v167, v15, v246
	v_fmac_f32_e32 v168, v9, v247
	v_fmac_f32_e32 v167, v10, v247
	ds_read_b128 v[2:5], v19 offset:33088
	ds_read_b128 v[234:237], v19 offset:33104
	ds_read_b128 v[238:241], v19 offset:33120
	ds_read_b128 v[244:247], v19 offset:33136
	v_mul_f32_e64 v249, |v168|, s84
	v_mul_f32_e64 v231, |v167|, s84
	v_exp_f32_e32 v249, v249
	v_exp_f32_e32 v231, v231
	v_min_f32_e32 v248, 0, v168
	v_min_f32_e32 v230, 0, v167
	v_add_f32_e32 v249, 1.0, v249
	v_add_f32_e32 v231, 1.0, v231
	v_cmp_gt_f32_e64 s[0:1], s31, v249
	v_cmp_gt_f32_e64 s[100:101], s31, v231
	s_nop 0
	v_cndmask_b32_e64 v250, 0, 32, s[0:1]
	v_cndmask_b32_e64 v232, 0, 32, s[100:101]
	v_ldexp_f32 v249, v249, v250
	v_ldexp_f32 v231, v231, v232
	v_log_f32_e32 v249, v249
	v_log_f32_e32 v231, v231
	v_mul_f32_e32 v250, 0x3f317217, v249
	v_mul_f32_e32 v232, 0x3f317217, v231
	v_fma_f32 v250, v249, s78, -v250
	v_fma_f32 v232, v231, s78, -v232
	v_fmac_f32_e32 v250, 0x3377d1cf, v249
	v_fmac_f32_e32 v232, 0x3377d1cf, v231
	v_fmac_f32_e32 v250, 0x3f317217, v249
	v_fmac_f32_e32 v232, 0x3f317217, v231
	v_cmp_lt_f32_e64 s[88:89], |v249|, s79
	v_cndmask_b32_e64 v251, 0, v198, s[0:1]
	v_cndmask_b32_e64 v233, 0, v198, s[100:101]
	v_cndmask_b32_e64 v249, v249, v250, s[88:89]
	v_cmp_lt_f32_e64 s[88:89], |v231|, s79
	v_sub_f32_e32 v249, v249, v251
	v_sub_f32_e32 v171, v248, v249
	v_cndmask_b32_e64 v231, v231, v232, s[88:89]
	v_sub_f32_e32 v231, v231, v233
	v_sub_f32_e32 v174, v230, v231
	v_fmamk_f32 v168, v171, 0x3d800000, v162
	v_fmamk_f32 v167, v174, 0x3d800000, v161
	s_waitcnt lgkmcnt(3)
	v_fma_f32 v169, v60, v2, v69
	v_fma_f32 v170, v61, v2, v68
	v_fmac_f32_e32 v169, v62, v3
	v_fmac_f32_e32 v170, v63, v3
	v_fmac_f32_e32 v169, v64, v4
	v_fmac_f32_e32 v170, v65, v4
	v_fmac_f32_e32 v169, v66, v5
	v_fmac_f32_e32 v170, v67, v5
	s_waitcnt lgkmcnt(2)
	v_fmac_f32_e32 v169, v47, v234
	v_fmac_f32_e32 v170, v46, v234
	v_fmac_f32_e32 v169, v17, v235
	v_fmac_f32_e32 v170, v16, v235
	v_fmac_f32_e32 v169, v52, v236
	v_fmac_f32_e32 v170, v53, v236
	v_fmac_f32_e32 v169, v54, v237
	v_fmac_f32_e32 v170, v55, v237
	s_waitcnt lgkmcnt(1)
	v_fmac_f32_e32 v169, v48, v238
	v_fmac_f32_e32 v170, v49, v238
	v_fmac_f32_e32 v169, v50, v239
	v_fmac_f32_e32 v170, v51, v239
	v_fmac_f32_e32 v169, v56, v240
	v_fmac_f32_e32 v170, v57, v240
	v_fmac_f32_e32 v169, v58, v241
	v_fmac_f32_e32 v170, v59, v241
	s_waitcnt lgkmcnt(0)
	v_fmac_f32_e32 v169, v12, v244
	v_fmac_f32_e32 v170, v13, v244
	v_fmac_f32_e32 v169, v6, v245
	v_fmac_f32_e32 v170, v7, v245
	v_fmac_f32_e32 v169, v14, v246
	v_fmac_f32_e32 v170, v15, v246
	v_fmac_f32_e32 v169, v9, v247
	v_fmac_f32_e32 v170, v10, v247
	ds_read_b128 v[2:5], v19 offset:33152
	ds_read_b128 v[234:237], v19 offset:33168
	ds_read_b128 v[238:241], v19 offset:33184
	ds_read_b128 v[244:247], v19 offset:33200
	v_mul_f32_e64 v249, |v169|, s84
	v_mul_f32_e64 v231, |v170|, s84
	v_exp_f32_e32 v249, v249
	v_exp_f32_e32 v231, v231
	v_min_f32_e32 v248, 0, v169
	v_min_f32_e32 v230, 0, v170
	v_add_f32_e32 v249, 1.0, v249
	v_add_f32_e32 v231, 1.0, v231
	v_cmp_gt_f32_e64 s[0:1], s31, v249
	v_cmp_gt_f32_e64 s[100:101], s31, v231
	s_nop 0
	v_cndmask_b32_e64 v250, 0, 32, s[0:1]
	v_cndmask_b32_e64 v232, 0, 32, s[100:101]
	v_ldexp_f32 v249, v249, v250
	v_ldexp_f32 v231, v231, v232
	v_log_f32_e32 v249, v249
	v_log_f32_e32 v231, v231
	v_mul_f32_e32 v250, 0x3f317217, v249
	v_mul_f32_e32 v232, 0x3f317217, v231
	v_fma_f32 v250, v249, s78, -v250
	v_fma_f32 v232, v231, s78, -v232
	v_fmac_f32_e32 v250, 0x3377d1cf, v249
	v_fmac_f32_e32 v232, 0x3377d1cf, v231
	v_fmac_f32_e32 v250, 0x3f317217, v249
	v_fmac_f32_e32 v232, 0x3f317217, v231
	v_cmp_lt_f32_e64 s[88:89], |v249|, s79
	v_cndmask_b32_e64 v251, 0, v198, s[0:1]
	v_cndmask_b32_e64 v233, 0, v198, s[100:101]
	v_cndmask_b32_e64 v249, v249, v250, s[88:89]
	v_cmp_lt_f32_e64 s[88:89], |v231|, s79
	v_sub_f32_e32 v249, v249, v251
	v_sub_f32_e32 v177, v248, v249
	v_cndmask_b32_e64 v231, v231, v232, s[88:89]
	v_sub_f32_e32 v231, v231, v233
	v_sub_f32_e32 v180, v230, v231
	v_fmamk_f32 v170, v177, 0x3d800000, v168
	v_fmamk_f32 v169, v180, 0x3d800000, v167
	s_waitcnt lgkmcnt(3)
	v_fma_f32 v172, v60, v2, v69
	v_fma_f32 v173, v61, v2, v68
	v_fmac_f32_e32 v172, v62, v3
	v_fmac_f32_e32 v173, v63, v3
	v_fmac_f32_e32 v172, v64, v4
	v_fmac_f32_e32 v173, v65, v4
	v_fmac_f32_e32 v172, v66, v5
	v_fmac_f32_e32 v173, v67, v5
	s_waitcnt lgkmcnt(2)
	v_fmac_f32_e32 v172, v47, v234
	v_fmac_f32_e32 v173, v46, v234
	v_fmac_f32_e32 v172, v17, v235
	v_fmac_f32_e32 v173, v16, v235
	v_fmac_f32_e32 v172, v52, v236
	v_fmac_f32_e32 v173, v53, v236
	v_fmac_f32_e32 v172, v54, v237
	v_fmac_f32_e32 v173, v55, v237
	s_waitcnt lgkmcnt(1)
	v_fmac_f32_e32 v172, v48, v238
	v_fmac_f32_e32 v173, v49, v238
	v_fmac_f32_e32 v172, v50, v239
	v_fmac_f32_e32 v173, v51, v239
	v_fmac_f32_e32 v172, v56, v240
	v_fmac_f32_e32 v173, v57, v240
	v_fmac_f32_e32 v172, v58, v241
	v_fmac_f32_e32 v173, v59, v241
	s_waitcnt lgkmcnt(0)
	v_fmac_f32_e32 v172, v12, v244
	v_fmac_f32_e32 v173, v13, v244
	v_fmac_f32_e32 v172, v6, v245
	v_fmac_f32_e32 v173, v7, v245
	v_fmac_f32_e32 v172, v14, v246
	v_fmac_f32_e32 v173, v15, v246
	v_fmac_f32_e32 v172, v9, v247
	v_fmac_f32_e32 v173, v10, v247
	ds_read_b128 v[2:5], v19 offset:33216
	ds_read_b128 v[234:237], v19 offset:33232
	ds_read_b128 v[238:241], v19 offset:33248
	ds_read_b128 v[244:247], v19 offset:33264
	v_mul_f32_e64 v249, |v172|, s84
	v_mul_f32_e64 v231, |v173|, s84
	v_exp_f32_e32 v249, v249
	v_exp_f32_e32 v231, v231
	v_min_f32_e32 v248, 0, v172
	v_min_f32_e32 v230, 0, v173
	v_add_f32_e32 v249, 1.0, v249
	v_add_f32_e32 v231, 1.0, v231
	v_cmp_gt_f32_e64 s[0:1], s31, v249
	v_cmp_gt_f32_e64 s[100:101], s31, v231
	s_nop 0
	v_cndmask_b32_e64 v250, 0, 32, s[0:1]
	v_cndmask_b32_e64 v232, 0, 32, s[100:101]
	v_ldexp_f32 v249, v249, v250
	v_ldexp_f32 v231, v231, v232
	v_log_f32_e32 v249, v249
	v_log_f32_e32 v231, v231
	v_mul_f32_e32 v250, 0x3f317217, v249
	v_mul_f32_e32 v232, 0x3f317217, v231
	v_fma_f32 v250, v249, s78, -v250
	v_fma_f32 v232, v231, s78, -v232
	v_fmac_f32_e32 v250, 0x3377d1cf, v249
	v_fmac_f32_e32 v232, 0x3377d1cf, v231
	v_fmac_f32_e32 v250, 0x3f317217, v249
	v_fmac_f32_e32 v232, 0x3f317217, v231
	v_cmp_lt_f32_e64 s[88:89], |v249|, s79
	v_cndmask_b32_e64 v251, 0, v198, s[0:1]
	v_cndmask_b32_e64 v233, 0, v198, s[100:101]
	v_cndmask_b32_e64 v249, v249, v250, s[88:89]
	v_cmp_lt_f32_e64 s[88:89], |v231|, s79
	v_sub_f32_e32 v249, v249, v251
	v_sub_f32_e32 v183, v248, v249
	v_cndmask_b32_e64 v231, v231, v232, s[88:89]
	v_sub_f32_e32 v231, v231, v233
	v_sub_f32_e32 v199, v230, v231
	v_fmamk_f32 v173, v183, 0x3d800000, v170
	v_fmamk_f32 v172, v199, 0x3d800000, v169
	s_waitcnt lgkmcnt(3)
	v_fma_f32 v175, v60, v2, v69
	v_fma_f32 v176, v61, v2, v68
	v_fmac_f32_e32 v175, v62, v3
	v_fmac_f32_e32 v176, v63, v3
	v_fmac_f32_e32 v175, v64, v4
	v_fmac_f32_e32 v176, v65, v4
	v_fmac_f32_e32 v175, v66, v5
	v_fmac_f32_e32 v176, v67, v5
	s_waitcnt lgkmcnt(2)
	v_fmac_f32_e32 v175, v47, v234
	v_fmac_f32_e32 v176, v46, v234
	v_fmac_f32_e32 v175, v17, v235
	v_fmac_f32_e32 v176, v16, v235
	v_fmac_f32_e32 v175, v52, v236
	v_fmac_f32_e32 v176, v53, v236
	v_fmac_f32_e32 v175, v54, v237
	v_fmac_f32_e32 v176, v55, v237
	s_waitcnt lgkmcnt(1)
	v_fmac_f32_e32 v175, v48, v238
	v_fmac_f32_e32 v176, v49, v238
	v_fmac_f32_e32 v175, v50, v239
	v_fmac_f32_e32 v176, v51, v239
	v_fmac_f32_e32 v175, v56, v240
	v_fmac_f32_e32 v176, v57, v240
	v_fmac_f32_e32 v175, v58, v241
	v_fmac_f32_e32 v176, v59, v241
	s_waitcnt lgkmcnt(0)
	v_fmac_f32_e32 v175, v12, v244
	v_fmac_f32_e32 v176, v13, v244
	v_fmac_f32_e32 v175, v6, v245
	v_fmac_f32_e32 v176, v7, v245
	v_fmac_f32_e32 v175, v14, v246
	v_fmac_f32_e32 v176, v15, v246
	v_fmac_f32_e32 v175, v9, v247
	v_fmac_f32_e32 v176, v10, v247
	ds_read_b128 v[2:5], v19 offset:33280
	ds_read_b128 v[234:237], v19 offset:33296
	ds_read_b128 v[238:241], v19 offset:33312
	ds_read_b128 v[244:247], v19 offset:33328
	v_mul_f32_e64 v249, |v175|, s84
	v_mul_f32_e64 v231, |v176|, s84
	v_exp_f32_e32 v249, v249
	v_exp_f32_e32 v231, v231
	v_min_f32_e32 v248, 0, v175
	v_min_f32_e32 v230, 0, v176
	v_add_f32_e32 v249, 1.0, v249
	v_add_f32_e32 v231, 1.0, v231
	v_cmp_gt_f32_e64 s[0:1], s31, v249
	v_cmp_gt_f32_e64 s[100:101], s31, v231
	s_nop 0
	v_cndmask_b32_e64 v250, 0, 32, s[0:1]
	v_cndmask_b32_e64 v232, 0, 32, s[100:101]
	v_ldexp_f32 v249, v249, v250
	v_ldexp_f32 v231, v231, v232
	v_log_f32_e32 v249, v249
	v_log_f32_e32 v231, v231
	v_mul_f32_e32 v250, 0x3f317217, v249
	v_mul_f32_e32 v232, 0x3f317217, v231
	v_fma_f32 v250, v249, s78, -v250
	v_fma_f32 v232, v231, s78, -v232
	v_fmac_f32_e32 v250, 0x3377d1cf, v249
	v_fmac_f32_e32 v232, 0x3377d1cf, v231
	v_fmac_f32_e32 v250, 0x3f317217, v249
	v_fmac_f32_e32 v232, 0x3f317217, v231
	v_cmp_lt_f32_e64 s[88:89], |v249|, s79
	v_cndmask_b32_e64 v251, 0, v198, s[0:1]
	v_cndmask_b32_e64 v233, 0, v198, s[100:101]
	v_cndmask_b32_e64 v249, v249, v250, s[88:89]
	v_cmp_lt_f32_e64 s[88:89], |v231|, s79
	v_sub_f32_e32 v249, v249, v251
	v_sub_f32_e32 v202, v248, v249
	v_cndmask_b32_e64 v231, v231, v232, s[88:89]
	v_sub_f32_e32 v231, v231, v233
	v_sub_f32_e32 v203, v230, v231
	v_fmamk_f32 v176, v202, 0x3d800000, v173
	v_fmamk_f32 v175, v203, 0x3d800000, v172
	s_waitcnt lgkmcnt(3)
	v_fma_f32 v178, v60, v2, v69
	v_fma_f32 v179, v61, v2, v68
	v_fmac_f32_e32 v178, v62, v3
	v_fmac_f32_e32 v179, v63, v3
	v_fmac_f32_e32 v178, v64, v4
	v_fmac_f32_e32 v179, v65, v4
	v_fmac_f32_e32 v178, v66, v5
	v_fmac_f32_e32 v179, v67, v5
	s_waitcnt lgkmcnt(2)
	v_fmac_f32_e32 v178, v47, v234
	v_fmac_f32_e32 v179, v46, v234
	v_fmac_f32_e32 v178, v17, v235
	v_fmac_f32_e32 v179, v16, v235
	v_fmac_f32_e32 v178, v52, v236
	v_fmac_f32_e32 v179, v53, v236
	v_fmac_f32_e32 v178, v54, v237
	v_fmac_f32_e32 v179, v55, v237
	s_waitcnt lgkmcnt(1)
	v_fmac_f32_e32 v178, v48, v238
	v_fmac_f32_e32 v179, v49, v238
	v_fmac_f32_e32 v178, v50, v239
	v_fmac_f32_e32 v179, v51, v239
	v_fmac_f32_e32 v178, v56, v240
	v_fmac_f32_e32 v179, v57, v240
	v_fmac_f32_e32 v178, v58, v241
	v_fmac_f32_e32 v179, v59, v241
	s_waitcnt lgkmcnt(0)
	v_fmac_f32_e32 v178, v12, v244
	v_fmac_f32_e32 v179, v13, v244
	v_fmac_f32_e32 v178, v6, v245
	v_fmac_f32_e32 v179, v7, v245
	v_fmac_f32_e32 v178, v14, v246
	v_fmac_f32_e32 v179, v15, v246
	v_fmac_f32_e32 v178, v9, v247
	v_fmac_f32_e32 v179, v10, v247
	ds_read_b128 v[2:5], v19 offset:33344
	ds_read_b128 v[234:237], v19 offset:33360
	ds_read_b128 v[238:241], v19 offset:33376
	ds_read_b128 v[244:247], v19 offset:33392
	v_mul_f32_e64 v249, |v178|, s84
	v_mul_f32_e64 v231, |v179|, s84
	v_exp_f32_e32 v249, v249
	v_exp_f32_e32 v231, v231
	v_min_f32_e32 v248, 0, v178
	v_min_f32_e32 v230, 0, v179
	v_add_f32_e32 v249, 1.0, v249
	v_add_f32_e32 v231, 1.0, v231
	v_cmp_gt_f32_e64 s[0:1], s31, v249
	v_cmp_gt_f32_e64 s[100:101], s31, v231
	s_nop 0
	v_cndmask_b32_e64 v250, 0, 32, s[0:1]
	v_cndmask_b32_e64 v232, 0, 32, s[100:101]
	v_ldexp_f32 v249, v249, v250
	v_ldexp_f32 v231, v231, v232
	v_log_f32_e32 v249, v249
	v_log_f32_e32 v231, v231
	v_mul_f32_e32 v250, 0x3f317217, v249
	v_mul_f32_e32 v232, 0x3f317217, v231
	v_fma_f32 v250, v249, s78, -v250
	v_fma_f32 v232, v231, s78, -v232
	v_fmac_f32_e32 v250, 0x3377d1cf, v249
	v_fmac_f32_e32 v232, 0x3377d1cf, v231
	v_fmac_f32_e32 v250, 0x3f317217, v249
	v_fmac_f32_e32 v232, 0x3f317217, v231
	v_cmp_lt_f32_e64 s[88:89], |v249|, s79
	v_cndmask_b32_e64 v251, 0, v198, s[0:1]
	v_cndmask_b32_e64 v233, 0, v198, s[100:101]
	v_cndmask_b32_e64 v249, v249, v250, s[88:89]
	v_cmp_lt_f32_e64 s[88:89], |v231|, s79
	v_sub_f32_e32 v249, v249, v251
	v_sub_f32_e32 v206, v248, v249
	v_cndmask_b32_e64 v231, v231, v232, s[88:89]
	v_sub_f32_e32 v231, v231, v233
	v_sub_f32_e32 v207, v230, v231
	v_fmamk_f32 v179, v206, 0x3d800000, v176
	v_fmamk_f32 v178, v207, 0x3d800000, v175
	s_waitcnt lgkmcnt(3)
	v_fma_f32 v181, v60, v2, v69
	v_fma_f32 v182, v61, v2, v68
	v_fmac_f32_e32 v181, v62, v3
	v_fmac_f32_e32 v182, v63, v3
	v_fmac_f32_e32 v181, v64, v4
	v_fmac_f32_e32 v182, v65, v4
	v_fmac_f32_e32 v181, v66, v5
	v_fmac_f32_e32 v182, v67, v5
	s_waitcnt lgkmcnt(2)
	v_fmac_f32_e32 v181, v47, v234
	v_fmac_f32_e32 v182, v46, v234
	v_fmac_f32_e32 v181, v17, v235
	v_fmac_f32_e32 v182, v16, v235
	v_fmac_f32_e32 v181, v52, v236
	v_fmac_f32_e32 v182, v53, v236
	v_fmac_f32_e32 v181, v54, v237
	v_fmac_f32_e32 v182, v55, v237
	s_waitcnt lgkmcnt(1)
	v_fmac_f32_e32 v181, v48, v238
	v_fmac_f32_e32 v182, v49, v238
	v_fmac_f32_e32 v181, v50, v239
	v_fmac_f32_e32 v182, v51, v239
	v_fmac_f32_e32 v181, v56, v240
	v_fmac_f32_e32 v182, v57, v240
	v_fmac_f32_e32 v181, v58, v241
	v_fmac_f32_e32 v182, v59, v241
	s_waitcnt lgkmcnt(0)
	v_fmac_f32_e32 v181, v12, v244
	v_fmac_f32_e32 v182, v13, v244
	v_fmac_f32_e32 v181, v6, v245
	v_fmac_f32_e32 v182, v7, v245
	v_fmac_f32_e32 v181, v14, v246
	v_fmac_f32_e32 v182, v15, v246
	v_fmac_f32_e32 v181, v9, v247
	v_fmac_f32_e32 v182, v10, v247
	ds_read_b128 v[2:5], v19 offset:33408
	ds_read_b128 v[234:237], v19 offset:33424
	ds_read_b128 v[238:241], v19 offset:33440
	ds_read_b128 v[244:247], v19 offset:33456
	v_mul_f32_e64 v249, |v181|, s84
	v_mul_f32_e64 v231, |v182|, s84
	v_exp_f32_e32 v249, v249
	v_exp_f32_e32 v231, v231
	v_min_f32_e32 v248, 0, v181
	v_min_f32_e32 v230, 0, v182
	v_add_f32_e32 v249, 1.0, v249
	v_add_f32_e32 v231, 1.0, v231
	v_cmp_gt_f32_e64 s[0:1], s31, v249
	v_cmp_gt_f32_e64 s[100:101], s31, v231
	s_nop 0
	v_cndmask_b32_e64 v250, 0, 32, s[0:1]
	v_cndmask_b32_e64 v232, 0, 32, s[100:101]
	v_ldexp_f32 v249, v249, v250
	v_ldexp_f32 v231, v231, v232
	v_log_f32_e32 v249, v249
	v_log_f32_e32 v231, v231
	v_mul_f32_e32 v250, 0x3f317217, v249
	v_mul_f32_e32 v232, 0x3f317217, v231
	v_fma_f32 v250, v249, s78, -v250
	v_fma_f32 v232, v231, s78, -v232
	v_fmac_f32_e32 v250, 0x3377d1cf, v249
	v_fmac_f32_e32 v232, 0x3377d1cf, v231
	v_fmac_f32_e32 v250, 0x3f317217, v249
	v_fmac_f32_e32 v232, 0x3f317217, v231
	v_cmp_lt_f32_e64 s[88:89], |v249|, s79
	v_cndmask_b32_e64 v251, 0, v198, s[0:1]
	v_cndmask_b32_e64 v233, 0, v198, s[100:101]
	v_cndmask_b32_e64 v249, v249, v250, s[88:89]
	v_cmp_lt_f32_e64 s[88:89], |v231|, s79
	v_sub_f32_e32 v249, v249, v251
	v_sub_f32_e32 v210, v248, v249
	v_cndmask_b32_e64 v231, v231, v232, s[88:89]
	v_sub_f32_e32 v231, v231, v233
	v_sub_f32_e32 v211, v230, v231
	v_fmamk_f32 v182, v210, 0x3d800000, v179
	v_fmamk_f32 v181, v211, 0x3d800000, v178
	s_waitcnt lgkmcnt(3)
	v_fma_f32 v192, v60, v2, v69
	v_fma_f32 v193, v61, v2, v68
	v_fmac_f32_e32 v192, v62, v3
	v_fmac_f32_e32 v193, v63, v3
	v_fmac_f32_e32 v192, v64, v4
	v_fmac_f32_e32 v193, v65, v4
	v_fmac_f32_e32 v192, v66, v5
	v_fmac_f32_e32 v193, v67, v5
	s_waitcnt lgkmcnt(2)
	v_fmac_f32_e32 v192, v47, v234
	v_fmac_f32_e32 v193, v46, v234
	v_fmac_f32_e32 v192, v17, v235
	v_fmac_f32_e32 v193, v16, v235
	v_fmac_f32_e32 v192, v52, v236
	v_fmac_f32_e32 v193, v53, v236
	v_fmac_f32_e32 v192, v54, v237
	v_fmac_f32_e32 v193, v55, v237
	s_waitcnt lgkmcnt(1)
	v_fmac_f32_e32 v192, v48, v238
	v_fmac_f32_e32 v193, v49, v238
	v_fmac_f32_e32 v192, v50, v239
	v_fmac_f32_e32 v193, v51, v239
	v_fmac_f32_e32 v192, v56, v240
	v_fmac_f32_e32 v193, v57, v240
	v_fmac_f32_e32 v192, v58, v241
	v_fmac_f32_e32 v193, v59, v241
	s_waitcnt lgkmcnt(0)
	v_fmac_f32_e32 v192, v12, v244
	v_fmac_f32_e32 v193, v13, v244
	v_fmac_f32_e32 v192, v6, v245
	v_fmac_f32_e32 v193, v7, v245
	v_fmac_f32_e32 v192, v14, v246
	v_fmac_f32_e32 v193, v15, v246
	v_fmac_f32_e32 v192, v9, v247
	v_fmac_f32_e32 v193, v10, v247
	ds_read_b128 v[2:5], v19 offset:33472
	ds_read_b128 v[234:237], v19 offset:33488
	ds_read_b128 v[238:241], v19 offset:33504
	ds_read_b128 v[244:247], v19 offset:33520
	v_mul_f32_e64 v249, |v192|, s84
	v_mul_f32_e64 v231, |v193|, s84
	v_exp_f32_e32 v249, v249
	v_exp_f32_e32 v231, v231
	v_min_f32_e32 v248, 0, v192
	v_min_f32_e32 v230, 0, v193
	v_add_f32_e32 v249, 1.0, v249
	v_add_f32_e32 v231, 1.0, v231
	v_cmp_gt_f32_e64 s[0:1], s31, v249
	v_cmp_gt_f32_e64 s[100:101], s31, v231
	s_nop 0
	v_cndmask_b32_e64 v250, 0, 32, s[0:1]
	v_cndmask_b32_e64 v232, 0, 32, s[100:101]
	v_ldexp_f32 v249, v249, v250
	v_ldexp_f32 v231, v231, v232
	v_log_f32_e32 v249, v249
	v_log_f32_e32 v231, v231
	v_mul_f32_e32 v250, 0x3f317217, v249
	v_mul_f32_e32 v232, 0x3f317217, v231
	v_fma_f32 v250, v249, s78, -v250
	v_fma_f32 v232, v231, s78, -v232
	v_fmac_f32_e32 v250, 0x3377d1cf, v249
	v_fmac_f32_e32 v232, 0x3377d1cf, v231
	v_fmac_f32_e32 v250, 0x3f317217, v249
	v_fmac_f32_e32 v232, 0x3f317217, v231
	v_cmp_lt_f32_e64 s[88:89], |v249|, s79
	v_cndmask_b32_e64 v251, 0, v198, s[0:1]
	v_cndmask_b32_e64 v233, 0, v198, s[100:101]
	v_cndmask_b32_e64 v249, v249, v250, s[88:89]
	v_cmp_lt_f32_e64 s[88:89], |v231|, s79
	v_sub_f32_e32 v249, v249, v251
	v_sub_f32_e32 v214, v248, v249
	v_cndmask_b32_e64 v231, v231, v232, s[88:89]
	v_sub_f32_e32 v231, v231, v233
	v_sub_f32_e32 v217, v230, v231
	v_fmamk_f32 v201, v214, 0x3d800000, v182
	v_fmamk_f32 v200, v217, 0x3d800000, v181
	s_waitcnt lgkmcnt(3)
	v_fma_f32 v192, v60, v2, v69
	v_fma_f32 v193, v61, v2, v68
	v_fmac_f32_e32 v192, v62, v3
	v_fmac_f32_e32 v193, v63, v3
	v_fmac_f32_e32 v192, v64, v4
	v_fmac_f32_e32 v193, v65, v4
	v_fmac_f32_e32 v192, v66, v5
	v_fmac_f32_e32 v193, v67, v5
	s_waitcnt lgkmcnt(2)
	v_fmac_f32_e32 v192, v47, v234
	v_fmac_f32_e32 v193, v46, v234
	v_fmac_f32_e32 v192, v17, v235
	v_fmac_f32_e32 v193, v16, v235
	v_fmac_f32_e32 v192, v52, v236
	v_fmac_f32_e32 v193, v53, v236
	v_fmac_f32_e32 v192, v54, v237
	v_fmac_f32_e32 v193, v55, v237
	s_waitcnt lgkmcnt(1)
	v_fmac_f32_e32 v192, v48, v238
	v_fmac_f32_e32 v193, v49, v238
	v_fmac_f32_e32 v192, v50, v239
	v_fmac_f32_e32 v193, v51, v239
	v_fmac_f32_e32 v192, v56, v240
	v_fmac_f32_e32 v193, v57, v240
	v_fmac_f32_e32 v192, v58, v241
	v_fmac_f32_e32 v193, v59, v241
	s_waitcnt lgkmcnt(0)
	v_fmac_f32_e32 v192, v12, v244
	v_fmac_f32_e32 v193, v13, v244
	v_fmac_f32_e32 v192, v6, v245
	v_fmac_f32_e32 v193, v7, v245
	v_fmac_f32_e32 v192, v14, v246
	v_fmac_f32_e32 v193, v15, v246
	v_fmac_f32_e32 v192, v9, v247
	v_fmac_f32_e32 v193, v10, v247
	ds_read_b128 v[2:5], v19 offset:33536
	ds_read_b128 v[234:237], v19 offset:33552
	ds_read_b128 v[238:241], v19 offset:33568
	ds_read_b128 v[244:247], v19 offset:33584
	v_mul_f32_e64 v249, |v192|, s84
	v_mul_f32_e64 v231, |v193|, s84
	v_exp_f32_e32 v249, v249
	v_exp_f32_e32 v231, v231
	v_min_f32_e32 v248, 0, v192
	v_min_f32_e32 v230, 0, v193
	v_add_f32_e32 v249, 1.0, v249
	v_add_f32_e32 v231, 1.0, v231
	v_cmp_gt_f32_e64 s[0:1], s31, v249
	v_cmp_gt_f32_e64 s[100:101], s31, v231
	s_nop 0
	v_cndmask_b32_e64 v250, 0, 32, s[0:1]
	v_cndmask_b32_e64 v232, 0, 32, s[100:101]
	v_ldexp_f32 v249, v249, v250
	v_ldexp_f32 v231, v231, v232
	v_log_f32_e32 v249, v249
	v_log_f32_e32 v231, v231
	v_mul_f32_e32 v250, 0x3f317217, v249
	v_mul_f32_e32 v232, 0x3f317217, v231
	v_fma_f32 v250, v249, s78, -v250
	v_fma_f32 v232, v231, s78, -v232
	v_fmac_f32_e32 v250, 0x3377d1cf, v249
	v_fmac_f32_e32 v232, 0x3377d1cf, v231
	v_fmac_f32_e32 v250, 0x3f317217, v249
	v_fmac_f32_e32 v232, 0x3f317217, v231
	v_cmp_lt_f32_e64 s[88:89], |v249|, s79
	v_cndmask_b32_e64 v251, 0, v198, s[0:1]
	v_cndmask_b32_e64 v233, 0, v198, s[100:101]
	v_cndmask_b32_e64 v249, v249, v250, s[88:89]
	v_cmp_lt_f32_e64 s[88:89], |v231|, s79
	v_sub_f32_e32 v249, v249, v251
	v_sub_f32_e32 v218, v248, v249
	v_cndmask_b32_e64 v231, v231, v232, s[88:89]
	v_sub_f32_e32 v231, v231, v233
	v_sub_f32_e32 v223, v230, v231
	v_fmamk_f32 v205, v218, 0x3d800000, v201
	v_fmamk_f32 v204, v223, 0x3d800000, v200
	s_waitcnt lgkmcnt(3)
	v_fma_f32 v192, v60, v2, v69
	v_fma_f32 v193, v61, v2, v68
	v_fmac_f32_e32 v192, v62, v3
	v_fmac_f32_e32 v193, v63, v3
	v_fmac_f32_e32 v192, v64, v4
	v_fmac_f32_e32 v193, v65, v4
	v_fmac_f32_e32 v192, v66, v5
	v_fmac_f32_e32 v193, v67, v5
	s_waitcnt lgkmcnt(2)
	v_fmac_f32_e32 v192, v47, v234
	v_fmac_f32_e32 v193, v46, v234
	v_fmac_f32_e32 v192, v17, v235
	v_fmac_f32_e32 v193, v16, v235
	v_fmac_f32_e32 v192, v52, v236
	v_fmac_f32_e32 v193, v53, v236
	v_fmac_f32_e32 v192, v54, v237
	v_fmac_f32_e32 v193, v55, v237
	s_waitcnt lgkmcnt(1)
	v_fmac_f32_e32 v192, v48, v238
	v_fmac_f32_e32 v193, v49, v238
	v_fmac_f32_e32 v192, v50, v239
	v_fmac_f32_e32 v193, v51, v239
	v_fmac_f32_e32 v192, v56, v240
	v_fmac_f32_e32 v193, v57, v240
	v_fmac_f32_e32 v192, v58, v241
	v_fmac_f32_e32 v193, v59, v241
	s_waitcnt lgkmcnt(0)
	v_fmac_f32_e32 v192, v12, v244
	v_fmac_f32_e32 v193, v13, v244
	v_fmac_f32_e32 v192, v6, v245
	v_fmac_f32_e32 v193, v7, v245
	v_fmac_f32_e32 v192, v14, v246
	v_fmac_f32_e32 v193, v15, v246
	v_fmac_f32_e32 v192, v9, v247
	v_fmac_f32_e32 v193, v10, v247
	ds_read_b128 v[2:5], v19 offset:33600
	ds_read_b128 v[234:237], v19 offset:33616
	ds_read_b128 v[238:241], v19 offset:33632
	ds_read_b128 v[244:247], v19 offset:33648
	v_mul_f32_e64 v249, |v192|, s84
	v_mul_f32_e64 v231, |v193|, s84
	v_exp_f32_e32 v249, v249
	v_exp_f32_e32 v231, v231
	v_min_f32_e32 v248, 0, v192
	v_min_f32_e32 v230, 0, v193
	v_add_f32_e32 v249, 1.0, v249
	v_add_f32_e32 v231, 1.0, v231
	v_cmp_gt_f32_e64 s[0:1], s31, v249
	v_cmp_gt_f32_e64 s[100:101], s31, v231
	s_nop 0
	v_cndmask_b32_e64 v250, 0, 32, s[0:1]
	v_cndmask_b32_e64 v232, 0, 32, s[100:101]
	v_ldexp_f32 v249, v249, v250
	v_ldexp_f32 v231, v231, v232
	v_log_f32_e32 v249, v249
	v_log_f32_e32 v231, v231
	v_mul_f32_e32 v250, 0x3f317217, v249
	v_mul_f32_e32 v232, 0x3f317217, v231
	v_fma_f32 v250, v249, s78, -v250
	v_fma_f32 v232, v231, s78, -v232
	v_fmac_f32_e32 v250, 0x3377d1cf, v249
	v_fmac_f32_e32 v232, 0x3377d1cf, v231
	v_fmac_f32_e32 v250, 0x3f317217, v249
	v_fmac_f32_e32 v232, 0x3f317217, v231
	v_cmp_lt_f32_e64 s[88:89], |v249|, s79
	v_cndmask_b32_e64 v251, 0, v198, s[0:1]
	v_cndmask_b32_e64 v233, 0, v198, s[100:101]
	v_cndmask_b32_e64 v249, v249, v250, s[88:89]
	v_cmp_lt_f32_e64 s[88:89], |v231|, s79
	v_sub_f32_e32 v249, v249, v251
	v_sub_f32_e32 v224, v248, v249
	v_cndmask_b32_e64 v231, v231, v232, s[88:89]
	v_sub_f32_e32 v231, v231, v233
	v_sub_f32_e32 v225, v230, v231
	v_fmamk_f32 v209, v224, 0x3d800000, v205
	v_fmamk_f32 v208, v225, 0x3d800000, v204
	s_waitcnt lgkmcnt(3)
	v_fma_f32 v192, v60, v2, v69
	v_fma_f32 v193, v61, v2, v68
	v_fmac_f32_e32 v192, v62, v3
	v_fmac_f32_e32 v193, v63, v3
	v_fmac_f32_e32 v192, v64, v4
	v_fmac_f32_e32 v193, v65, v4
	v_fmac_f32_e32 v192, v66, v5
	v_fmac_f32_e32 v193, v67, v5
	s_waitcnt lgkmcnt(2)
	v_fmac_f32_e32 v192, v47, v234
	v_fmac_f32_e32 v193, v46, v234
	v_fmac_f32_e32 v192, v17, v235
	v_fmac_f32_e32 v193, v16, v235
	v_fmac_f32_e32 v192, v52, v236
	v_fmac_f32_e32 v193, v53, v236
	v_fmac_f32_e32 v192, v54, v237
	v_fmac_f32_e32 v193, v55, v237
	s_waitcnt lgkmcnt(1)
	v_fmac_f32_e32 v192, v48, v238
	v_fmac_f32_e32 v193, v49, v238
	v_fmac_f32_e32 v192, v50, v239
	v_fmac_f32_e32 v193, v51, v239
	v_fmac_f32_e32 v192, v56, v240
	v_fmac_f32_e32 v193, v57, v240
	v_fmac_f32_e32 v192, v58, v241
	v_fmac_f32_e32 v193, v59, v241
	s_waitcnt lgkmcnt(0)
	v_fmac_f32_e32 v192, v12, v244
	v_fmac_f32_e32 v193, v13, v244
	v_fmac_f32_e32 v192, v6, v245
	v_fmac_f32_e32 v193, v7, v245
	v_fmac_f32_e32 v192, v14, v246
	v_fmac_f32_e32 v193, v15, v246
	v_fmac_f32_e32 v192, v9, v247
	v_fmac_f32_e32 v193, v10, v247
	ds_read_b128 v[2:5], v19 offset:33664
	ds_read_b128 v[234:237], v19 offset:33680
	ds_read_b128 v[238:241], v19 offset:33696
	ds_read_b128 v[244:247], v19 offset:33712
	v_mul_f32_e64 v249, |v192|, s84
	v_mul_f32_e64 v231, |v193|, s84
	v_exp_f32_e32 v249, v249
	v_exp_f32_e32 v231, v231
	v_min_f32_e32 v248, 0, v192
	v_min_f32_e32 v230, 0, v193
	v_add_f32_e32 v249, 1.0, v249
	v_add_f32_e32 v231, 1.0, v231
	v_cmp_gt_f32_e64 s[0:1], s31, v249
	v_cmp_gt_f32_e64 s[100:101], s31, v231
	s_nop 0
	v_cndmask_b32_e64 v250, 0, 32, s[0:1]
	v_cndmask_b32_e64 v232, 0, 32, s[100:101]
	v_ldexp_f32 v249, v249, v250
	v_ldexp_f32 v231, v231, v232
	v_log_f32_e32 v249, v249
	v_log_f32_e32 v231, v231
	v_mul_f32_e32 v250, 0x3f317217, v249
	v_mul_f32_e32 v232, 0x3f317217, v231
	v_fma_f32 v250, v249, s78, -v250
	v_fma_f32 v232, v231, s78, -v232
	v_fmac_f32_e32 v250, 0x3377d1cf, v249
	v_fmac_f32_e32 v232, 0x3377d1cf, v231
	v_fmac_f32_e32 v250, 0x3f317217, v249
	v_fmac_f32_e32 v232, 0x3f317217, v231
	v_cmp_lt_f32_e64 s[88:89], |v249|, s79
	v_cndmask_b32_e64 v251, 0, v198, s[0:1]
	v_cndmask_b32_e64 v233, 0, v198, s[100:101]
	v_cndmask_b32_e64 v249, v249, v250, s[88:89]
	v_cmp_lt_f32_e64 s[88:89], |v231|, s79
	v_sub_f32_e32 v249, v249, v251
	v_sub_f32_e32 v226, v248, v249
	v_cndmask_b32_e64 v231, v231, v232, s[88:89]
	v_sub_f32_e32 v231, v231, v233
	v_sub_f32_e32 v227, v230, v231
	v_fmamk_f32 v213, v226, 0x3d800000, v209
	v_fmamk_f32 v212, v227, 0x3d800000, v208
	s_waitcnt lgkmcnt(3)
	v_fma_f32 v192, v60, v2, v69
	v_fma_f32 v193, v61, v2, v68
	v_fmac_f32_e32 v192, v62, v3
	v_fmac_f32_e32 v193, v63, v3
	v_fmac_f32_e32 v192, v64, v4
	v_fmac_f32_e32 v193, v65, v4
	v_fmac_f32_e32 v192, v66, v5
	v_fmac_f32_e32 v193, v67, v5
	s_waitcnt lgkmcnt(2)
	v_fmac_f32_e32 v192, v47, v234
	v_fmac_f32_e32 v193, v46, v234
	v_fmac_f32_e32 v192, v17, v235
	v_fmac_f32_e32 v193, v16, v235
	v_fmac_f32_e32 v192, v52, v236
	v_fmac_f32_e32 v193, v53, v236
	v_fmac_f32_e32 v192, v54, v237
	v_fmac_f32_e32 v193, v55, v237
	s_waitcnt lgkmcnt(1)
	v_fmac_f32_e32 v192, v48, v238
	v_fmac_f32_e32 v193, v49, v238
	v_fmac_f32_e32 v192, v50, v239
	v_fmac_f32_e32 v193, v51, v239
	v_fmac_f32_e32 v192, v56, v240
	v_fmac_f32_e32 v193, v57, v240
	v_fmac_f32_e32 v192, v58, v241
	v_fmac_f32_e32 v193, v59, v241
	s_waitcnt lgkmcnt(0)
	v_fmac_f32_e32 v192, v12, v244
	v_fmac_f32_e32 v193, v13, v244
	v_fmac_f32_e32 v192, v6, v245
	v_fmac_f32_e32 v193, v7, v245
	v_fmac_f32_e32 v192, v14, v246
	v_fmac_f32_e32 v193, v15, v246
	v_fmac_f32_e32 v192, v9, v247
	v_fmac_f32_e32 v193, v10, v247
	v_mul_f32_e64 v249, |v192|, s84
	v_mul_f32_e64 v231, |v193|, s84
	v_exp_f32_e32 v249, v249
	v_exp_f32_e32 v231, v231
	v_min_f32_e32 v248, 0, v192
	v_min_f32_e32 v230, 0, v193
	v_add_f32_e32 v249, 1.0, v249
	v_add_f32_e32 v231, 1.0, v231
	v_cmp_gt_f32_e64 s[0:1], s31, v249
	v_cmp_gt_f32_e64 s[100:101], s31, v231
	s_nop 0
	v_cndmask_b32_e64 v250, 0, 32, s[0:1]
	v_cndmask_b32_e64 v232, 0, 32, s[100:101]
	v_ldexp_f32 v249, v249, v250
	v_ldexp_f32 v231, v231, v232
	v_log_f32_e32 v249, v249
	v_log_f32_e32 v231, v231
	v_mul_f32_e32 v250, 0x3f317217, v249
	v_mul_f32_e32 v232, 0x3f317217, v231
	v_fma_f32 v250, v249, s78, -v250
	v_fma_f32 v232, v231, s78, -v232
	v_fmac_f32_e32 v250, 0x3377d1cf, v249
	v_fmac_f32_e32 v232, 0x3377d1cf, v231
	v_fmac_f32_e32 v250, 0x3f317217, v249
	v_fmac_f32_e32 v232, 0x3f317217, v231
	v_cmp_lt_f32_e64 s[88:89], |v249|, s79
	v_cndmask_b32_e64 v251, 0, v198, s[0:1]
	v_cndmask_b32_e64 v233, 0, v198, s[100:101]
	v_cndmask_b32_e64 v249, v249, v250, s[88:89]
	v_cmp_lt_f32_e64 s[88:89], |v231|, s79
	v_sub_f32_e32 v249, v249, v251
	v_sub_f32_e32 v228, v248, v249
	v_cndmask_b32_e64 v231, v231, v232, s[88:89]
	v_sub_f32_e32 v231, v231, v233
	v_sub_f32_e32 v229, v230, v231
	v_fmamk_f32 v216, v228, 0x3d800000, v213
	v_fmamk_f32 v215, v229, 0x3d800000, v212
	ds_read_b128 v[2:5], v19 offset:33728
	s_waitcnt lgkmcnt(0)
	v_fmac_f32_e32 v69, v60, v2
	v_fmac_f32_e32 v68, v61, v2
	v_fmac_f32_e32 v69, v62, v3
	v_fmac_f32_e32 v68, v63, v3
	v_fmac_f32_e32 v69, v64, v4
	v_fmac_f32_e32 v68, v65, v4
	v_fmac_f32_e32 v69, v66, v5
	v_fmac_f32_e32 v68, v67, v5
	ds_read_b128 v[2:5], v19 offset:33744
	s_waitcnt lgkmcnt(0)
	v_fmac_f32_e32 v69, v47, v2
	v_fmac_f32_e32 v68, v46, v2
	v_fmac_f32_e32 v69, v17, v3
	v_fmac_f32_e32 v68, v16, v3
	v_fmac_f32_e32 v69, v52, v4
	v_fmac_f32_e32 v68, v53, v4
	v_fmac_f32_e32 v69, v54, v5
	v_fmac_f32_e32 v68, v55, v5
	ds_read_b128 v[2:5], v19 offset:33760
	v_mov_b64_e32 v[46:47], s[58:59]
	s_waitcnt lgkmcnt(0)
	v_fmac_f32_e32 v69, v48, v2
	v_fmac_f32_e32 v68, v49, v2
	v_fmac_f32_e32 v69, v50, v3
	v_fmac_f32_e32 v68, v51, v3
	v_fmac_f32_e32 v69, v56, v4
	v_fmac_f32_e32 v68, v57, v4
	v_fmac_f32_e32 v69, v58, v5
	v_fmac_f32_e32 v68, v59, v5
	ds_read_b128 v[2:5], v19 offset:33776
	s_waitcnt lgkmcnt(0)
	v_fmac_f32_e32 v69, v12, v2
	v_fmac_f32_e32 v69, v6, v3
	v_fmac_f32_e32 v69, v14, v4
	v_fmac_f32_e32 v68, v13, v2
	v_fmac_f32_e32 v69, v9, v5
	v_fmac_f32_e32 v68, v7, v3
	v_mul_f32_e64 v3, |v69|, s84
	v_exp_f32_e32 v3, v3
	v_fmac_f32_e32 v68, v15, v4
	v_fmac_f32_e32 v68, v10, v5
	v_min_f32_e32 v2, 0, v69
	v_add_f32_e32 v3, 1.0, v3
	v_cmp_gt_f32_e64 s[0:1], s31, v3
	s_nop 1
	v_cndmask_b32_e64 v4, 0, 32, s[0:1]
	v_ldexp_f32 v3, v3, v4
	v_log_f32_e32 v3, v3
	s_nop 0
	v_mul_f32_e32 v4, 0x3f317217, v3
	v_fma_f32 v4, v3, s78, -v4
	v_fmac_f32_e32 v4, 0x3377d1cf, v3
	v_fmac_f32_e32 v4, 0x3f317217, v3
	v_cmp_lt_f32_e64 s[88:89], |v3|, s79
	s_nop 1
	v_cndmask_b32_e64 v3, v3, v4, s[88:89]
	v_cndmask_b32_e64 v4, 0, v198, s[0:1]
	v_sub_f32_e32 v3, v3, v4
	v_sub_f32_e32 v9, v2, v3
	v_mul_f32_e64 v3, |v68|, s84
	v_exp_f32_e32 v3, v3
	v_min_f32_e32 v2, 0, v68
	v_fmamk_f32 v220, v9, 0x3d800000, v216
	v_add_f32_e32 v3, 1.0, v3
	v_cmp_gt_f32_e64 s[0:1], s31, v3
	s_nop 1
	v_cndmask_b32_e64 v4, 0, 32, s[0:1]
	v_ldexp_f32 v3, v3, v4
	v_log_f32_e32 v3, v3
	s_nop 0
	v_mul_f32_e32 v4, 0x3f317217, v3
	v_fma_f32 v4, v3, s78, -v4
	v_fmac_f32_e32 v4, 0x3377d1cf, v3
	v_fmac_f32_e32 v4, 0x3f317217, v3
	v_cmp_lt_f32_e64 s[88:89], |v3|, s79
	s_nop 1
	v_cndmask_b32_e64 v3, v3, v4, s[88:89]
	v_cndmask_b32_e64 v4, 0, v198, s[0:1]
	v_sub_f32_e32 v3, v3, v4
	v_sub_f32_e32 v14, v2, v3
	v_fmamk_f32 v219, v14, 0x3d800000, v215
	ds_write2st64_b32 v23, v220, v219 offset0:144 offset1:145
	s_waitcnt lgkmcnt(0)
	s_barrier
	ds_read2st64_b32 v[2:3], v22 offset0:144 offset1:145
	ds_read2st64_b32 v[6:7], v22 offset0:146 offset1:147
	ds_read2st64_b32 v[4:5], v22 offset0:148 offset1:149
	s_waitcnt lgkmcnt(2)
	v_add_f32_e32 v10, 0, v2
	v_add_f32_e32 v13, 0, v3
	s_waitcnt lgkmcnt(1)
	v_add_f32_e32 v2, v10, v6
	v_add_f32_e32 v3, v13, v7
	s_waitcnt lgkmcnt(0)
	v_add_f32_e32 v12, v2, v4
	v_add_f32_e32 v15, v3, v5
	ds_read2st64_b32 v[2:3], v22 offset0:150 offset1:151
	s_waitcnt lgkmcnt(0)
	v_add_f32_e32 v12, v12, v2
	v_add_f32_e32 v15, v15, v3
	v_mul_f32_e32 v12, 0x3fb8aa3b, v12
	v_exp_f32_e32 v221, v12
	v_mul_f32_e32 v12, 0x3fb8aa3b, v15
	v_exp_f32_e32 v222, v12
	s_and_saveexec_b64 s[0:1], s[6:7]
	s_cbranch_execz .LBB0_224
	s_ashr_i32 s5, s58, 31
	s_mov_b32 s4, s58
	v_mov_b64_e32 v[46:47], s[4:5]
	global_store_dword v[36:37], v221, off
	global_store_dword v[36:37], v222, off offset:256
	s_branch .LBB0_224
